# prompt attention QK^T: K-fragment LDS reads issued 8 / 5 fragments ahead with counted waits instead of read-wait-MFMA per fragment
# speedup vs baseline: 1.0062x; 1.0046x over previous
.LBB0_870:
	s_and_b32 s8, s20, 1
	s_lshl_b32 s9, s8, 15
	s_add_i32 s29, s9, 0
	s_mul_i32 s30, s8, 0x2800
	v_add_u32_e32 v52, s29, v207
	v_add_u32_e32 v185, v52, v206
	v_add_u32_e32 v2, s29, v208
	v_add_u32_e32 v183, v2, v206
	v_add_u32_e32 v52, s29, v209
	v_add_u32_e32 v184, v52, v206
	v_add_u32_e32 v2, s29, v210
	v_add_u32_e32 v2, v2, v206
	v_add_u32_e32 v182, s30, v222
	s_add_i32 s20, s27, 0xffffffa2
	s_cmp_gt_i32 s20, s24
	s_cselect_b64 s[8:9], -1, 0
	s_cmp_le_i32 s20, s24
	s_cselect_b64 s[20:21], -1, 0
	ds_read_b128 v[84:87], v185
	ds_read_b128 v[88:91], v185 offset:8192
	ds_read_b128 v[92:95], v183
	ds_read_b128 v[96:99], v183 offset:8192
	ds_read_b128 v[100:103], v184
	ds_read_b128 v[104:107], v184 offset:8192
	ds_read_b128 v[108:111], v2
	ds_read_b128 v[112:115], v2 offset:8192
	s_waitcnt lgkmcnt(7)
	v_mfma_f32_32x32x16_bf16 v[52:67], v[84:87], v[144:147], v[20:35]
	ds_read_b128 v[84:87], v182
	s_waitcnt lgkmcnt(7)
	v_mfma_f32_32x32x16_bf16 v[68:83], v[88:91], v[144:147], v[20:35]
	ds_read_b128 v[88:91], v182 offset:2560
	s_waitcnt lgkmcnt(7)
	v_mfma_f32_32x32x16_bf16 v[52:67], v[92:95], v[148:151], v[52:67]
	ds_read_b128 v[92:95], v182 offset:32
	s_waitcnt lgkmcnt(7)
	v_mfma_f32_32x32x16_bf16 v[68:83], v[96:99], v[148:151], v[68:83]
	ds_read_b128 v[96:99], v182 offset:2592
	s_waitcnt lgkmcnt(7)
	v_mfma_f32_32x32x16_bf16 v[52:67], v[100:103], v[152:155], v[52:67]
	s_waitcnt lgkmcnt(6)
	v_mfma_f32_32x32x16_bf16 v[68:83], v[104:107], v[152:155], v[68:83]
	s_waitcnt lgkmcnt(5)
	v_mfma_f32_32x32x16_bf16 v[52:67], v[108:111], v[156:159], v[52:67]
	s_waitcnt lgkmcnt(4)
	v_mfma_f32_32x32x16_bf16 v[68:83], v[112:115], v[156:159], v[68:83]
	ds_read_b128 v[224:227], v185 offset:16384
	ds_read_b128 v[228:231], v185 offset:24576
	ds_read_b128 v[232:235], v183 offset:16384
	ds_read_b128 v[236:239], v183 offset:24576
	ds_read_b128 v[244:247], v184 offset:16384
	s_waitcnt lgkmcnt(8)
	v_mfma_f32_32x32x16_bf16 v[52:67], v[84:87], v[136:139], v[52:67]
	s_waitcnt lgkmcnt(7)
	v_mfma_f32_32x32x16_bf16 v[68:83], v[88:91], v[136:139], v[68:83]
	s_waitcnt lgkmcnt(6)
	v_mfma_f32_32x32x16_bf16 v[52:67], v[92:95], v[140:143], v[52:67]
	s_waitcnt lgkmcnt(5)
	v_mfma_f32_32x32x16_bf16 v[68:83], v[96:99], v[140:143], v[68:83]
	s_and_b64 vcc, exec, s[8:9]
	s_cbranch_vccz .Lpa_hi
	v_mov_b64_e32 v[100:101], v[20:21]
	v_mov_b64_e32 v[102:103], v[22:23]
	v_mov_b64_e32 v[104:105], v[24:25]
	v_mov_b64_e32 v[106:107], v[26:27]
	v_mov_b64_e32 v[108:109], v[28:29]
	v_mov_b64_e32 v[110:111], v[30:31]
	v_mov_b64_e32 v[112:113], v[32:33]
	v_mov_b64_e32 v[114:115], v[34:35]
	v_mov_b64_e32 v[84:85], v[20:21]
	v_mov_b64_e32 v[86:87], v[22:23]
	v_mov_b64_e32 v[88:89], v[24:25]
	v_mov_b64_e32 v[90:91], v[26:27]
	v_mov_b64_e32 v[92:93], v[28:29]
	v_mov_b64_e32 v[94:95], v[30:31]
	v_mov_b64_e32 v[96:97], v[32:33]
	v_mov_b64_e32 v[98:99], v[34:35]
	s_waitcnt lgkmcnt(0)
	s_branch .LBB0_872
.Lpa_hi:
	s_waitcnt lgkmcnt(4)
	v_mfma_f32_32x32x16_bf16 v[100:115], v[224:227], v[144:147], v[20:35]
	ds_read_b128 v[224:227], v184 offset:24576
	s_waitcnt lgkmcnt(4)
	v_mfma_f32_32x32x16_bf16 v[84:99], v[228:231], v[144:147], v[20:35]
	ds_read_b128 v[228:231], v2 offset:16384
	s_waitcnt lgkmcnt(4)
	v_mfma_f32_32x32x16_bf16 v[100:115], v[232:235], v[148:151], v[100:115]
	ds_read_b128 v[232:235], v2 offset:24576
	s_waitcnt lgkmcnt(4)
	v_mfma_f32_32x32x16_bf16 v[84:99], v[236:239], v[148:151], v[84:99]
	ds_read_b128 v[236:239], v182 offset:5120
	s_waitcnt lgkmcnt(4)
	v_mfma_f32_32x32x16_bf16 v[100:115], v[244:247], v[152:155], v[100:115]
	ds_read_b128 v[244:247], v182 offset:7680
	s_waitcnt lgkmcnt(4)
	v_mfma_f32_32x32x16_bf16 v[84:99], v[224:227], v[152:155], v[84:99]
	ds_read_b128 v[224:227], v182 offset:5152
	s_waitcnt lgkmcnt(4)
	v_mfma_f32_32x32x16_bf16 v[100:115], v[228:231], v[156:159], v[100:115]
	ds_read_b128 v[228:231], v182 offset:7712
	s_waitcnt lgkmcnt(4)
	v_mfma_f32_32x32x16_bf16 v[84:99], v[232:235], v[156:159], v[84:99]
	s_waitcnt lgkmcnt(3)
	v_mfma_f32_32x32x16_bf16 v[100:115], v[236:239], v[136:139], v[100:115]
	s_waitcnt lgkmcnt(2)
	v_mfma_f32_32x32x16_bf16 v[84:99], v[244:247], v[136:139], v[84:99]
	s_waitcnt lgkmcnt(1)
	v_mfma_f32_32x32x16_bf16 v[100:115], v[224:227], v[140:143], v[100:115]
	s_waitcnt lgkmcnt(0)
	v_mfma_f32_32x32x16_bf16 v[84:99], v[228:231], v[140:143], v[84:99]
